# P1 slack stagger: the 48 workgroups with 5 tiles (cid>>3 >= 26) start the in-proj GEMM 14us late to de-phase their epilogue bursts
# speedup vs baseline: 1.0046x; 1.0046x over previous
.LBB0_244:
	v_readlane_b32 s0, v246, 4
	v_readlane_b32 s1, v246, 5
	s_cmp_lt_i32 s0, 2
	s_cselect_b64 s[0:1], -1, 0
	s_and_b64 s[2:3], s[0:1], s[4:5]
	s_andn2_b64 vcc, exec, s[2:3]
	s_cbranch_vccnz .LBB0_482
	s_lshr_b32 s8, s30, 3
	s_cmp_lt_u32 s8, 26
	s_cbranch_scc1 .Lstg1_done
	s_sleep 127
	s_sleep 127
	s_sleep 127
	s_sleep 70
.Lstg1_done:
	s_add_u32 s8, s22, 0x880000
	s_addc_u32 s9, s23, 0
	s_cmpk_gt_i32 s30, 0x5ab
	v_readfirstlane_b32 s40, v202
	s_cbranch_scc0 .LBB0_248
	s_add_i32 s6, s30, 0xfffffa54
	s_mov_b64 s[4:5], 0
	s_cmp_lt_u32 s6, 32
	s_mov_b64 s[2:3], 0
	s_cbranch_scc0 .LBB0_249
	s_and_b32 s14, s6, 7
	s_lshr_b32 s10, s6, 3
	s_mov_b64 s[2:3], -1
	s_mov_b32 s41, 1
	s_branch .LBB0_249
